# v17 + diff attention output epilogue: last 12 gated-merge chunks' 24 loads issued together into dead VGPRs with exact in-order waits (were 12 serialized load->vmcnt(0)->store round trips)
# baseline (speedup 1.0000x reference)
; __device__ __forceinline__ int fresh_tid(int wave_s) { return wave_s * 64 + lane_id(); }
;     ...
;     float lt = lrun;
;     if (MODE == 1) lt += __builtin_amdgcn_exp2f(sink2 - mrun);
;     const float inv = 1.f / lt;
; #pragma unroll
;     for (int db = 0; db < NDB; ++db)
; #pragma unroll
;         for (int r = 0; r < 16; ++r) o[db][r] *= inv;
; __global__ void __launch_bounds__(512) fwd_megakernel(Args a) {
;     ...
;                     float ss = 0.f;
;                     const int t3 = fresh_tid(wave_s), l3 = t3 & 63;
;                     const f32x4* scr = (const f32x4*)(scr_blk + (size_t)t3 * 64);
; #pragma unroll
;                     for (int db = 0; db < 4; ++db)
;                     {
; #pragma unroll
;                       for (int j = 0; j < 4; ++j) { const f32x4 t4 = scr[db * 4 + j];
; #pragma unroll
;                             for (int e = 0; e < 4; ++e) { const float v = t4[e] - lam * o[db][4 * j + e]; o[db][4 * j + e] = v; ss += v * v; } }
;                       __builtin_amdgcn_sched_barrier(0); }
;                     ss += __shfl_xor(ss, 32);
;                     const float rs = rsqrtf(ss * (1.f / 128.f) + EPS) * lut[520];
;                     const int hl = l3 >> 5;
; #pragma unroll
;                     for (int db = 0; db < 4; ++db)
;                     {
; #pragma unroll
;                       for (int rg = 0; rg < 4; ++rg) { const f32x4 gn = *(const f32x4*)(subln + 32 * db + 8 * rg + 4 * hl);
.LBB0_892:
	v_div_scale_f32 v0, s[0:1], v144, v144, 1.0
	v_rcp_f32_e32 v2, v0
	v_readlane_b32 s0, v252, 32
	v_readlane_b32 s1, v252, 33
	v_fma_f32 v3, -v0, v2, 1.0
	v_fmac_f32_e32 v2, v3, v2
	v_div_scale_f32 v3, vcc, 1.0, v144, 1.0
	v_mul_f32_e32 v4, v3, v2
	v_fma_f32 v5, -v0, v4, v3
	v_fmac_f32_e32 v4, v5, v2
	v_fma_f32 v0, -v0, v4, v3
	v_div_fmas_f32 v0, v0, v2, v4
	v_div_fixup_f32 v206, v0, v144, 1.0
	v_mbcnt_lo_u32_b32 v0, -1, 0
	v_mbcnt_hi_u32_b32 v0, -1, v0
	s_nop 0
	v_add_u32_e32 v2, s92, v0
	v_ashrrev_i32_e32 v3, 31, v2
	v_lshlrev_b64 v[2:3], 8, v[2:3]
	v_lshl_add_u64 v[6:7], s[0:1], 0, v[2:3]
	global_load_dwordx4 v[172:175], v[6:7], off offset:48
	global_load_dwordx4 v[176:179], v[6:7], off offset:32
	global_load_dwordx4 v[180:183], v[6:7], off offset:16
	global_load_dwordx4 v[184:187], v[6:7], off
	global_load_dwordx4 v[152:155], v[6:7], off offset:112
	global_load_dwordx4 v[160:163], v[6:7], off offset:96
	global_load_dwordx4 v[164:167], v[6:7], off offset:80
	global_load_dwordx4 v[168:171], v[6:7], off offset:64
	global_load_dwordx4 v[136:139], v[6:7], off offset:176
	global_load_dwordx4 v[144:147], v[6:7], off offset:160
	global_load_dwordx4 v[148:151], v[6:7], off offset:144
	global_load_dwordx4 v[156:159], v[6:7], off offset:128
	global_load_dwordx4 v[2:5], v[6:7], off offset:240
	global_load_dwordx4 v[128:131], v[6:7], off offset:224
	global_load_dwordx4 v[132:135], v[6:7], off offset:208
	global_load_dwordx4 v[140:143], v[6:7], off offset:192
	v_pk_mul_f32 v[6:7], v[206:207], v[28:29] op_sel_hi:[0,1]
	v_pk_mul_f32 v[8:9], v[206:207], v[30:31] op_sel_hi:[0,1]
	s_waitcnt vmcnt(3)
	v_pk_fma_f32 v[188:189], s[50:51], v[6:7], v[2:3] neg_lo:[1,0,0] neg_hi:[1,0,0]
	v_pk_fma_f32 v[14:15], s[50:51], v[8:9], v[4:5] neg_lo:[1,0,0] neg_hi:[1,0,0]
	v_pk_mul_f32 v[194:195], v[188:189], v[188:189]
	v_pk_mul_f32 v[192:193], v[14:15], v[14:15]
	v_and_b32_e32 v3, 64, v241
	v_xor_b32_e32 v2, 32, v241
	v_add_u32_e32 v3, 64, v3
	v_cmp_lt_i32_e32 vcc, v2, v3
	ds_read_b32 v245, v1 offset:63520
	s_nop 0
	v_cndmask_b32_e32 v2, v241, v2, vcc
	v_lshlrev_b32_e32 v246, 2, v2
	v_lshrrev_b32_e32 v2, 3, v0
	v_and_b32_e32 v196, 4, v2
	v_lshlrev_b32_e32 v2, 2, v196
	global_load_dwordx4 v[96:99], v2, s[54:55]
	global_load_dwordx4 v[88:91], v2, s[54:55] offset:32
	global_load_dwordx4 v[80:83], v2, s[54:55] offset:64
	global_load_dwordx4 v[10:13], v2, s[54:55] offset:96
	global_load_dwordx4 v[124:127], v2, s[54:55] offset:128
	global_load_dwordx4 v[120:123], v2, s[54:55] offset:160
	global_load_dwordx4 v[116:119], v2, s[54:55] offset:192
	global_load_dwordx4 v[112:115], v2, s[54:55] offset:224
	global_load_dwordx4 v[108:111], v2, s[54:55] offset:256
	global_load_dwordx4 v[104:107], v2, s[54:55] offset:288
	global_load_dwordx4 v[100:103], v2, s[54:55] offset:320
	global_load_dwordx4 v[92:95], v2, s[54:55] offset:352
	global_load_dwordx4 v[84:87], v2, s[54:55] offset:384
	global_load_dwordx4 v[28:31], v2, s[54:55] offset:416
	global_load_dwordx4 v[6:9], v2, s[54:55] offset:448
	s_nop 0
	global_load_dwordx4 v[2:5], v2, s[54:55] offset:480
	s_add_u32 s0, s12, s43
	s_addc_u32 s1, s13, 0
	v_and_or_b32 v0, v0, 31, s0
	v_mov_b64_e32 v[190:191], s[96:97]
	s_movk_i32 s0, 0x4200
	s_mul_i32 s4, s1, 0x4200
	v_mad_u64_u32 v[190:191], s[0:1], v0, s0, v[190:191]
	v_add_u32_e32 v191, s4, v191
	s_lshl_b32 s40, s25, 1
	v_lshl_add_u64 v[190:191], v[190:191], 0, s[40:41]
	v_lshlrev_b32_e32 v0, 1, v196
	v_lshl_add_u64 v[208:209], v[190:191], 0, v[0:1]
	s_mov_b64 s[0:1], 0x3a00
	v_lshl_add_u64 v[190:191], v[208:209], 0, s[0:1]
	s_movk_i32 s0, 0x3000
	v_add_co_u32_e32 v212, vcc, s0, v208
	s_mov_b64 s[0:1], 0x2a00
	v_pk_mul_f32 v[218:219], v[206:207], v[32:33] op_sel_hi:[0,1]
	v_lshl_add_u64 v[32:33], v[208:209], 0, s[0:1]
	v_addc_co_u32_e32 v213, vcc, 0, v209, vcc
	v_pk_mul_f32 v[236:237], v[206:207], v[74:75] op_sel_hi:[0,1]
	v_pk_mul_f32 v[196:197], v[206:207], v[72:73] op_sel_hi:[0,1]
	v_pk_mul_f32 v[72:73], v[206:207], v[78:79] op_sel_hi:[0,1]
	v_pk_mul_f32 v[78:79], v[206:207], v[76:77] op_sel_hi:[0,1]
	v_pk_mul_f32 v[74:75], v[206:207], v[56:57] op_sel_hi:[0,1]
	v_pk_mul_f32 v[76:77], v[206:207], v[62:63] op_sel_hi:[0,1]
	global_load_dwordx2 v[56:57], v[190:191], off offset:16
	global_load_dwordx2 v[62:63], v[32:33], off offset:16
	global_load_dwordx2 v[198:199], v[212:213], off offset:2560
	global_load_dwordx2 v[200:201], v[190:191], off offset:32
	s_movk_i32 s0, 0x2000
	v_pk_mul_f32 v[216:217], v[206:207], v[64:65] op_sel_hi:[0,1]
	v_pk_mul_f32 v[64:65], v[206:207], v[48:49] op_sel_hi:[0,1]
	v_add_co_u32_e32 v48, vcc, s0, v208
	v_pk_mul_f32 v[220:221], v[206:207], v[40:41] op_sel_hi:[0,1]
	s_nop 0
	v_addc_co_u32_e32 v49, vcc, 0, v209, vcc
	global_load_dwordx2 v[202:203], v[48:49], off offset:2560
	global_load_dwordx2 v[208:209], v[32:33], off offset:32
	global_load_dwordx2 v[40:41], v[190:191], off offset:48
	v_pk_mul_f32 v[210:211], v[206:207], v[66:67] op_sel_hi:[0,1]
	v_pk_mul_f32 v[234:235], v[206:207], v[68:69] op_sel_hi:[0,1]
	v_pk_mul_f32 v[222:223], v[206:207], v[26:27] op_sel_hi:[0,1]
	v_pk_fma_f32 v[26:27], s[50:51], v[216:217], v[184:185] neg_lo:[1,0,0] neg_hi:[1,0,0]
	v_pk_mul_f32 v[70:71], v[206:207], v[70:71] op_sel_hi:[0,1]
	v_pk_mul_f32 v[50:51], v[206:207], v[50:51] op_sel_hi:[0,1]
	v_pk_mul_f32 v[54:55], v[206:207], v[54:55] op_sel_hi:[0,1]
	v_pk_mul_f32 v[66:67], v[206:207], v[52:53] op_sel_hi:[0,1]
	v_pk_mul_f32 v[68:69], v[206:207], v[58:59] op_sel_hi:[0,1]
	v_pk_mul_f32 v[214:215], v[206:207], v[60:61] op_sel_hi:[0,1]
	v_pk_mul_f32 v[34:35], v[206:207], v[34:35] op_sel_hi:[0,1]
	v_pk_mul_f32 v[38:39], v[206:207], v[38:39] op_sel_hi:[0,1]
; __device__ __forceinline__ float bflo(unsigned u) { return __uint_as_float(u << 16); }
; __device__ __forceinline__ float bfhi(unsigned u) { return __uint_as_float(u & 0xffff0000u); }
; __device__ __forceinline__ int fresh_tid(int wave_s) { return wave_s * 64 + lane_id(); }
; template <int DV, bool ACCUM>
; __device__ __forceinline__ void attn_store(const f32x16 (&o)[DV / 32], const bf16_t* gate_row, bf16_t* merged_row, int h) {
;     ...
;             const u32x2 g = *(const u32x2*)(gate_row + d);
;             float v0 = o[db][4 * rg + 0] * bflo(g.x), v1 = o[db][4 * rg + 1] * bfhi(g.x), v2 = o[db][4 * rg + 2] * bflo(g.y), v3 = o[db][4 * rg + 3] * bfhi(g.y);
;             if (ACCUM) { const u32x2 mm = *(const u32x2*)(merged_row + d); v0 += bflo(mm.x); v1 += bfhi(mm.x); v2 += bflo(mm.y); v3 += bfhi(mm.y); }
; __global__ void __launch_bounds__(512) fwd_megakernel(Args a) {
;     ...
;                     float ss = 0.f;
;                     const int t3 = fresh_tid(wave_s), l3 = t3 & 63;
;                     const f32x4* scr = (const f32x4*)(scr_blk + (size_t)t3 * 64);
; #pragma unroll
;                     for (int db = 0; db < 4; ++db)
;                     {
; #pragma unroll
;                       for (int j = 0; j < 4; ++j) { const f32x4 t4 = scr[db * 4 + j];
; #pragma unroll
;                             for (int e = 0; e < 4; ++e) { const float v = t4[e] - lam * o[db][4 * j + e]; o[db][4 * j + e] = v; ss += v * v; } }
;                       __builtin_amdgcn_sched_barrier(0); }
;                     ss += __shfl_xor(ss, 32);
;                     const float rs = rsqrtf(ss * (1.f / 128.f) + EPS) * lut[520];
	v_pk_mul_f32 v[36:37], v[206:207], v[36:37] op_sel_hi:[0,1]
	v_pk_mul_f32 v[42:43], v[206:207], v[42:43] op_sel_hi:[0,1]
	v_pk_mul_f32 v[46:47], v[206:207], v[46:47] op_sel_hi:[0,1]
	v_pk_mul_f32 v[228:229], v[206:207], v[44:45] op_sel_hi:[0,1]
	v_pk_mul_f32 v[230:231], v[206:207], v[18:19] op_sel_hi:[0,1]
	v_pk_mul_f32 v[232:233], v[206:207], v[16:17] op_sel_hi:[0,1]
	v_pk_mul_f32 v[224:225], v[206:207], v[22:23] op_sel_hi:[0,1]
	v_pk_mul_f32 v[226:227], v[206:207], v[20:21] op_sel_hi:[0,1]
	v_pk_mul_f32 v[206:207], v[206:207], v[24:25] op_sel_hi:[0,1]
	v_pk_fma_f32 v[22:23], s[50:51], v[210:211], v[186:187] neg_lo:[1,0,0] neg_hi:[1,0,0]
	v_pk_fma_f32 v[24:25], s[50:51], v[234:235], v[180:181] neg_lo:[1,0,0] neg_hi:[1,0,0]
	v_pk_mul_f32 v[180:181], v[26:27], v[26:27]
	v_pk_fma_f32 v[16:17], s[50:51], v[236:237], v[178:179] neg_lo:[1,0,0] neg_hi:[1,0,0]
	v_pk_mul_f32 v[178:179], v[22:23], v[22:23]
	v_add_f32_e32 v0, v180, v181
	v_add_f32_e32 v0, v0, v178
	v_pk_mul_f32 v[184:185], v[24:25], v[24:25]
	v_add_f32_e32 v0, v0, v179
	v_pk_fma_f32 v[18:19], s[50:51], v[70:71], v[182:183] neg_lo:[1,0,0] neg_hi:[1,0,0]
	v_add_f32_e32 v0, v0, v184
	v_pk_mul_f32 v[182:183], v[18:19], v[18:19]
	v_add_f32_e32 v0, v0, v185
	v_pk_fma_f32 v[20:21], s[50:51], v[196:197], v[176:177] neg_lo:[1,0,0] neg_hi:[1,0,0]
	v_add_f32_e32 v0, v0, v182
	v_pk_fma_f32 v[44:45], s[50:51], v[72:73], v[174:175] neg_lo:[1,0,0] neg_hi:[1,0,0]
	v_pk_fma_f32 v[176:177], s[50:51], v[78:79], v[172:173] neg_lo:[1,0,0] neg_hi:[1,0,0]
	v_add_f32_e32 v0, v0, v183
	v_pk_mul_f32 v[186:187], v[16:17], v[16:17]
	v_pk_fma_f32 v[74:75], s[50:51], v[74:75], v[160:161] neg_lo:[1,0,0] neg_hi:[1,0,0]
	v_pk_mul_f32 v[160:161], v[176:177], v[176:177]
	v_pk_fma_f32 v[66:67], s[50:51], v[66:67], v[164:165] neg_lo:[1,0,0] neg_hi:[1,0,0]
	v_pk_mul_f32 v[164:165], v[44:45], v[44:45]
	v_pk_fma_f32 v[64:65], s[50:51], v[64:65], v[168:169] neg_lo:[1,0,0] neg_hi:[1,0,0]
	v_pk_fma_f32 v[76:77], s[50:51], v[76:77], v[154:155] neg_lo:[1,0,0] neg_hi:[1,0,0]
	v_pk_mul_f32 v[154:155], v[64:65], v[64:65]
	v_pk_fma_f32 v[50:51], s[50:51], v[50:51], v[170:171] neg_lo:[1,0,0] neg_hi:[1,0,0]
	v_pk_fma_f32 v[68:69], s[50:51], v[68:69], v[162:163] neg_lo:[1,0,0] neg_hi:[1,0,0]
	v_pk_mul_f32 v[162:163], v[50:51], v[50:51]
	v_pk_fma_f32 v[34:35], s[50:51], v[34:35], v[158:159] neg_lo:[1,0,0] neg_hi:[1,0,0]
	v_pk_mul_f32 v[158:159], v[66:67], v[66:67]
	v_pk_fma_f32 v[54:55], s[50:51], v[54:55], v[166:167] neg_lo:[1,0,0] neg_hi:[1,0,0]
	v_pk_fma_f32 v[150:151], s[50:51], v[38:39], v[150:151] neg_lo:[1,0,0] neg_hi:[1,0,0]
	v_pk_mul_f32 v[38:39], v[74:75], v[74:75]
	v_pk_fma_f32 v[152:153], s[50:51], v[214:215], v[152:153] neg_lo:[1,0,0] neg_hi:[1,0,0]
	global_load_dwordx2 v[196:197], v[32:33], off offset:48
	v_pk_fma_f32 v[146:147], s[50:51], v[42:43], v[146:147] neg_lo:[1,0,0] neg_hi:[1,0,0]
	v_pk_mul_f32 v[42:43], v[152:153], v[152:153]
	v_pk_fma_f32 v[36:37], s[50:51], v[36:37], v[148:149] neg_lo:[1,0,0] neg_hi:[1,0,0]
	v_pk_mul_f32 v[148:149], v[76:77], v[76:77]
	v_pk_fma_f32 v[156:157], s[50:51], v[218:219], v[156:157] neg_lo:[1,0,0] neg_hi:[1,0,0]
	v_pk_fma_f32 v[138:139], s[50:51], v[46:47], v[138:139] neg_lo:[1,0,0] neg_hi:[1,0,0]
	v_pk_mul_f32 v[46:47], v[156:157], v[156:157]
	v_pk_mul_f32 v[212:213], v[36:37], v[36:37]
	v_pk_mul_f32 v[210:211], v[150:151], v[150:151]
	v_pk_fma_f32 v[144:145], s[50:51], v[220:221], v[144:145] neg_lo:[1,0,0] neg_hi:[1,0,0]
	v_pk_mul_f32 v[214:215], v[146:147], v[146:147]
	s_waitcnt vmcnt(7)
	v_lshlrev_b32_e32 v52, 16, v57
	s_waitcnt vmcnt(5)
	v_lshlrev_b32_e32 v72, 16, v199
	v_and_b32_e32 v73, 0xffff0000, v199
	v_lshlrev_b32_e32 v78, 16, v198
	v_and_b32_e32 v79, 0xffff0000, v198
	v_pk_mul_f32 v[198:199], v[20:21], v[20:21]
	v_and_b32_e32 v53, 0xffff0000, v57
	v_add_f32_e32 v0, v0, v198
	v_add_f32_e32 v0, v0, v199
	v_add_f32_e32 v0, v0, v186
	v_add_f32_e32 v0, v0, v187
	v_add_f32_e32 v0, v0, v160
	v_add_f32_e32 v0, v0, v161
	v_add_f32_e32 v0, v0, v164
	v_add_f32_e32 v0, v0, v165
	v_add_f32_e32 v0, v0, v154
	v_add_f32_e32 v0, v0, v155
	v_add_f32_e32 v0, v0, v162
	v_add_f32_e32 v0, v0, v163
	v_add_f32_e32 v0, v0, v158
	v_lshlrev_b32_e32 v58, 16, v56
	v_and_b32_e32 v59, 0xffff0000, v56
	s_waitcnt vmcnt(4)
	v_lshlrev_b32_e32 v56, 16, v201
	v_and_b32_e32 v57, 0xffff0000, v201
	v_lshlrev_b32_e32 v70, 16, v200
	v_and_b32_e32 v71, 0xffff0000, v200
	v_pk_mul_f32 v[200:201], v[54:55], v[54:55]
	v_add_f32_e32 v0, v0, v159
	v_add_f32_e32 v0, v0, v200
	v_add_f32_e32 v0, v0, v201
	v_add_f32_e32 v0, v0, v38
	s_waitcnt vmcnt(3)
	v_lshlrev_b32_e32 v172, 16, v202
	v_and_b32_e32 v173, 0xffff0000, v202
	v_lshlrev_b32_e32 v174, 16, v203
	v_and_b32_e32 v175, 0xffff0000, v203
	v_pk_mul_f32 v[202:203], v[68:69], v[68:69]
	v_add_f32_e32 v0, v0, v39
	v_add_f32_e32 v0, v0, v202
	v_add_f32_e32 v0, v0, v203
	v_add_f32_e32 v0, v0, v42
	v_add_f32_e32 v0, v0, v43
	v_add_f32_e32 v0, v0, v148
	v_add_f32_e32 v0, v0, v149
	v_add_f32_e32 v0, v0, v46
	s_waitcnt vmcnt(2)
; __device__ __forceinline__ int fresh_tid(int wave_s) { return wave_s * 64 + lane_id(); }
; __global__ void __launch_bounds__(512) fwd_megakernel(Args a) {
;     ...
;                     float ss = 0.f;
;                     const int t3 = fresh_tid(wave_s), l3 = t3 & 63;
;                     const f32x4* scr = (const f32x4*)(scr_blk + (size_t)t3 * 64);
; #pragma unroll
;                     for (int db = 0; db < 4; ++db)
;                     {
; #pragma unroll
;                       for (int j = 0; j < 4; ++j) { const f32x4 t4 = scr[db * 4 + j];
; #pragma unroll
;                             for (int e = 0; e < 4; ++e) { const float v = t4[e] - lam * o[db][4 * j + e]; o[db][4 * j + e] = v; ss += v * v; } }
;                       __builtin_amdgcn_sched_barrier(0); }
;                     ss += __shfl_xor(ss, 32);
;                     const float rs = rsqrtf(ss * (1.f / 128.f) + EPS) * lut[520];
;                     const int hl = l3 >> 5;
; #pragma unroll
;                     for (int db = 0; db < 4; ++db)
;                     {
; #pragma unroll
;                       for (int rg = 0; rg < 4; ++rg) { const f32x4 gn = *(const f32x4*)(subln + 32 * db + 8 * rg + 4 * hl);
; #pragma unroll
;                             for (int e = 0; e < 4; ++e) o[db][4 * rg + e] *= rs * gn[e]; }
	v_lshlrev_b32_e32 v168, 16, v208
	v_and_b32_e32 v169, 0xffff0000, v208
	v_lshlrev_b32_e32 v170, 16, v209
	v_and_b32_e32 v171, 0xffff0000, v209
	v_pk_mul_f32 v[208:209], v[34:35], v[34:35]
	v_add_f32_e32 v0, v0, v47
	v_add_f32_e32 v0, v0, v208
	v_add_f32_e32 v0, v0, v209
	v_add_f32_e32 v0, v0, v212
	v_add_f32_e32 v0, v0, v213
	v_add_f32_e32 v0, v0, v210
	v_pk_mul_f32 v[216:217], v[144:145], v[144:145]
	v_add_f32_e32 v0, v0, v211
	v_add_f32_e32 v0, v0, v216
	v_add_f32_e32 v0, v0, v217
	v_pk_fma_f32 v[136:137], s[50:51], v[228:229], v[136:137] neg_lo:[1,0,0] neg_hi:[1,0,0]
	v_add_f32_e32 v0, v0, v214
	v_pk_fma_f32 v[128:129], s[50:51], v[206:207], v[128:129] neg_lo:[1,0,0] neg_hi:[1,0,0]
	v_pk_mul_f32 v[206:207], v[136:137], v[136:137]
	v_add_f32_e32 v0, v0, v215
	v_add_f32_e32 v0, v0, v206
	v_pk_mul_f32 v[218:219], v[138:139], v[138:139]
	v_add_f32_e32 v0, v0, v207
	v_pk_fma_f32 v[140:141], s[50:51], v[232:233], v[140:141] neg_lo:[1,0,0] neg_hi:[1,0,0]
	v_add_f32_e32 v0, v0, v218
	v_pk_mul_f32 v[178:179], v[140:141], v[140:141]
	v_add_f32_e32 v0, v0, v219
	v_pk_fma_f32 v[142:143], s[50:51], v[230:231], v[142:143] neg_lo:[1,0,0] neg_hi:[1,0,0]
	v_add_f32_e32 v0, v0, v178
	v_pk_mul_f32 v[220:221], v[142:143], v[142:143]
	v_add_f32_e32 v0, v0, v179
	v_pk_fma_f32 v[132:133], s[50:51], v[226:227], v[132:133] neg_lo:[1,0,0] neg_hi:[1,0,0]
	v_add_f32_e32 v0, v0, v220
	v_pk_mul_f32 v[182:183], v[132:133], v[132:133]
	v_add_f32_e32 v0, v0, v221
	v_pk_fma_f32 v[134:135], s[50:51], v[224:225], v[134:135] neg_lo:[1,0,0] neg_hi:[1,0,0]
	v_add_f32_e32 v0, v0, v182
	v_pk_mul_f32 v[180:181], v[134:135], v[134:135]
	v_add_f32_e32 v0, v0, v183
	v_add_f32_e32 v0, v0, v180
	v_pk_mul_f32 v[186:187], v[128:129], v[128:129]
	v_add_f32_e32 v0, v0, v181
	v_pk_fma_f32 v[130:131], s[50:51], v[222:223], v[130:131] neg_lo:[1,0,0] neg_hi:[1,0,0]
	v_add_f32_e32 v0, v0, v186
	v_pk_mul_f32 v[184:185], v[130:131], v[130:131]
	v_add_f32_e32 v0, v0, v187
	v_add_f32_e32 v0, v0, v184
	v_add_f32_e32 v0, v0, v185
	v_add_f32_e32 v0, v0, v194
	v_add_f32_e32 v0, v0, v195
	v_add_f32_e32 v0, v0, v192
	v_add_f32_e32 v0, v0, v193
	ds_bpermute_b32 v38, v246, v0
	s_waitcnt vmcnt(1)
	v_lshlrev_b32_e32 v166, 16, v41
	v_and_b32_e32 v167, 0xffff0000, v41
	v_lshlrev_b32_e32 v148, 16, v40
	v_and_b32_e32 v149, 0xffff0000, v40
	s_waitcnt lgkmcnt(0)
	v_add_f32_e32 v0, v0, v38
	v_fmamk_f32 v0, v0, 0x3c000000, v239
	v_mul_f32_e32 v38, 0x4b800000, v0
	v_cmp_gt_f32_e32 vcc, s35, v0
	v_lshlrev_b32_e32 v60, 16, v62
	v_and_b32_e32 v61, 0xffff0000, v62
	v_cndmask_b32_e32 v0, v0, v38, vcc
	v_rsq_f32_e32 v0, v0
	v_lshlrev_b32_e32 v62, 16, v63
	v_and_b32_e32 v63, 0xffff0000, v63
	s_waitcnt vmcnt(0)
	v_lshlrev_b32_e32 v154, 16, v196
	v_mul_f32_e32 v38, 0x45800000, v0
	v_cndmask_b32_e32 v0, v0, v38, vcc
	v_mul_f32_e32 v0, v245, v0
	v_pk_mul_f32 v[10:11], v[0:1], v[10:11] op_sel_hi:[0,1]
	v_pk_mul_f32 v[160:161], v[10:11], v[176:177]
	v_pk_mul_f32 v[10:11], v[0:1], v[12:13] op_sel_hi:[0,1]
	v_pk_mul_f32 v[162:163], v[10:11], v[44:45]
	v_pk_mul_f32 v[10:11], v[0:1], v[124:125] op_sel_hi:[0,1]
	v_pk_mul_f32 v[64:65], v[10:11], v[64:65]
	v_pk_mul_f32 v[10:11], v[0:1], v[126:127] op_sel_hi:[0,1]
	v_pk_mul_f32 v[50:51], v[10:11], v[50:51]
	v_pk_mul_f32 v[10:11], v[0:1], v[120:121] op_sel_hi:[0,1]
	v_pk_mul_f32 v[66:67], v[10:11], v[66:67]
	v_pk_mul_f32 v[10:11], v[0:1], v[122:123] op_sel_hi:[0,1]
	v_pk_mul_f32 v[54:55], v[10:11], v[54:55]
	v_pk_mul_f32 v[10:11], v[0:1], v[116:117] op_sel_hi:[0,1]
	v_pk_mul_f32 v[74:75], v[10:11], v[74:75]
	v_pk_mul_f32 v[10:11], v[0:1], v[118:119] op_sel_hi:[0,1]
	v_pk_mul_f32 v[68:69], v[10:11], v[68:69]
	v_pk_mul_f32 v[10:11], v[0:1], v[112:113] op_sel_hi:[0,1]
	v_pk_mul_f32 v[46:47], v[10:11], v[152:153]
	v_pk_mul_f32 v[10:11], v[0:1], v[114:115] op_sel_hi:[0,1]
	v_pk_mul_f32 v[44:45], v[10:11], v[76:77]
	v_pk_mul_f32 v[10:11], v[0:1], v[108:109] op_sel_hi:[0,1]
	v_pk_mul_f32 v[42:43], v[10:11], v[156:157]
	v_pk_mul_f32 v[10:11], v[0:1], v[110:111] op_sel_hi:[0,1]
	v_pk_mul_f32 v[38:39], v[0:1], v[96:97] op_sel_hi:[0,1]
	v_pk_mul_f32 v[40:41], v[10:11], v[34:35]
	v_pk_mul_f32 v[10:11], v[0:1], v[104:105] op_sel_hi:[0,1]
	v_pk_mul_f32 v[96:97], v[38:39], v[26:27]
	v_pk_mul_f32 v[38:39], v[10:11], v[36:37]
	v_pk_mul_f32 v[10:11], v[0:1], v[106:107] op_sel_hi:[0,1]
	v_pk_mul_f32 v[36:37], v[10:11], v[150:151]
	v_pk_mul_f32 v[10:11], v[0:1], v[100:101] op_sel_hi:[0,1]
	v_pk_mul_f32 v[26:27], v[0:1], v[98:99] op_sel_hi:[0,1]
	v_pk_mul_f32 v[34:35], v[10:11], v[144:145]
	v_pk_mul_f32 v[10:11], v[0:1], v[102:103] op_sel_hi:[0,1]
	v_pk_mul_f32 v[98:99], v[26:27], v[22:23]
	v_pk_mul_f32 v[22:23], v[0:1], v[88:89] op_sel_hi:[0,1]
	v_pk_mul_f32 v[26:27], v[10:11], v[146:147]
	v_pk_mul_f32 v[10:11], v[0:1], v[92:93] op_sel_hi:[0,1]
	v_pk_mul_f32 v[88:89], v[22:23], v[24:25]
	v_pk_mul_f32 v[22:23], v[0:1], v[90:91] op_sel_hi:[0,1]
	v_pk_mul_f32 v[24:25], v[10:11], v[136:137]
	v_pk_mul_f32 v[10:11], v[0:1], v[94:95] op_sel_hi:[0,1]
	v_pk_mul_f32 v[90:91], v[22:23], v[18:19]
	v_pk_mul_f32 v[18:19], v[0:1], v[80:81] op_sel_hi:[0,1]
	v_pk_mul_f32 v[22:23], v[10:11], v[138:139]
	v_pk_mul_f32 v[10:11], v[0:1], v[84:85] op_sel_hi:[0,1]
	v_pk_mul_f32 v[80:81], v[18:19], v[20:21]
	v_pk_mul_f32 v[18:19], v[0:1], v[82:83] op_sel_hi:[0,1]
	v_pk_mul_f32 v[20:21], v[10:11], v[140:141]
	v_pk_mul_f32 v[10:11], v[0:1], v[86:87] op_sel_hi:[0,1]
	v_pk_mul_f32 v[82:83], v[18:19], v[16:17]
	v_pk_mul_f32 v[18:19], v[10:11], v[142:143]
	v_pk_mul_f32 v[10:11], v[0:1], v[28:29] op_sel_hi:[0,1]
	v_pk_mul_f32 v[16:17], v[10:11], v[132:133]
	v_pk_mul_f32 v[10:11], v[0:1], v[30:31] op_sel_hi:[0,1]
; __device__ __forceinline__ unsigned pk2(float lo, float hi) { f32x2_t v = {lo, hi}; bf16x2_t b = __builtin_convertvector(v, bf16x2_t); return __builtin_bit_cast(unsigned, b); }
; __device__ __forceinline__ float bflo(unsigned u) { return __uint_as_float(u << 16); }
; __device__ __forceinline__ float bfhi(unsigned u) { return __uint_as_float(u & 0xffff0000u); }
; template <int DV, bool ACCUM>
; __device__ __forceinline__ void attn_store(const f32x16 (&o)[DV / 32], const bf16_t* gate_row, bf16_t* merged_row, int h) {
; #pragma unroll
;     for (int db = 0; db < DV / 32; ++db)
; #pragma unroll
;         for (int rg = 0; rg < 4; ++rg) {
;             const int d = 32 * db + 8 * rg + 4 * h;
;             const u32x2 g = *(const u32x2*)(gate_row + d);
;             float v0 = o[db][4 * rg + 0] * bflo(g.x), v1 = o[db][4 * rg + 1] * bfhi(g.x), v2 = o[db][4 * rg + 2] * bflo(g.y), v3 = o[db][4 * rg + 3] * bfhi(g.y);
;             if (ACCUM) { const u32x2 mm = *(const u32x2*)(merged_row + d); v0 += bflo(mm.x); v1 += bfhi(mm.x); v2 += bflo(mm.y); v3 += bfhi(mm.y); }
;             u32x2 w; w.x = pk2(v0, v1); w.y = pk2(v2, v3);
;             *(u32x2*)(merged_row + d) = w;
;             if (rg == 3) __builtin_amdgcn_sched_barrier(0);
;         }
	v_pk_mul_f32 v[6:7], v[0:1], v[6:7] op_sel_hi:[0,1]
	v_pk_mul_f32 v[12:13], v[10:11], v[134:135]
	v_pk_mul_f32 v[10:11], v[6:7], v[128:129]
	v_pk_mul_f32 v[6:7], v[0:1], v[8:9] op_sel_hi:[0,1]
	v_pk_fma_f32 v[8:9], v[96:97], v[78:79], v[172:173]
	v_pk_fma_f32 v[28:29], v[98:99], v[72:73], v[174:175]
	v_cvt_pk_bf16_f32 v8, v8, v9
	v_cvt_pk_bf16_f32 v9, v28, v29
	global_store_dwordx2 v[48:49], v[8:9], off offset:2560
	v_pk_fma_f32 v[8:9], v[88:89], v[58:59], v[60:61]
	v_pk_fma_f32 v[28:29], v[90:91], v[52:53], v[62:63]
	v_cvt_pk_bf16_f32 v8, v8, v9
	v_cvt_pk_bf16_f32 v9, v28, v29
	global_store_dwordx2 v[32:33], v[8:9], off offset:16
	v_pk_fma_f32 v[8:9], v[80:81], v[70:71], v[168:169]
	v_pk_fma_f32 v[28:29], v[82:83], v[56:57], v[170:171]
	v_and_b32_e32 v155, 0xffff0000, v196
	v_lshlrev_b32_e32 v158, 16, v197
	v_and_b32_e32 v159, 0xffff0000, v197
	v_cvt_pk_bf16_f32 v8, v8, v9
	v_cvt_pk_bf16_f32 v9, v28, v29
	global_store_dwordx2 v[32:33], v[8:9], off offset:32
	v_pk_fma_f32 v[8:9], v[160:161], v[148:149], v[154:155]
	v_pk_fma_f32 v[28:29], v[162:163], v[166:167], v[158:159]
	v_cvt_pk_bf16_f32 v8, v8, v9
	v_cvt_pk_bf16_f32 v9, v28, v29
	v_pk_mul_f32 v[6:7], v[6:7], v[130:131]
	global_store_dwordx2 v[32:33], v[8:9], off offset:48
	global_load_dwordx2 v[100:101], v[190:191], off offset:64
	global_load_dwordx2 v[102:103], v[32:33], off offset:64
	global_load_dwordx2 v[104:105], v[190:191], off offset:80
	global_load_dwordx2 v[106:107], v[32:33], off offset:80
	global_load_dwordx2 v[108:109], v[190:191], off offset:96
	global_load_dwordx2 v[110:111], v[32:33], off offset:96
	global_load_dwordx2 v[112:113], v[190:191], off offset:112
	global_load_dwordx2 v[114:115], v[32:33], off offset:112
	global_load_dwordx2 v[116:117], v[190:191], off offset:128
	global_load_dwordx2 v[118:119], v[32:33], off offset:128
	global_load_dwordx2 v[120:121], v[190:191], off offset:144
	global_load_dwordx2 v[122:123], v[32:33], off offset:144
	global_load_dwordx2 v[124:125], v[190:191], off offset:160
	global_load_dwordx2 v[126:127], v[32:33], off offset:160
	global_load_dwordx2 v[128:129], v[190:191], off offset:176
	global_load_dwordx2 v[130:131], v[32:33], off offset:176
	global_load_dwordx2 v[132:133], v[190:191], off offset:192
	global_load_dwordx2 v[134:135], v[32:33], off offset:192
	global_load_dwordx2 v[136:137], v[190:191], off offset:208
	global_load_dwordx2 v[138:139], v[32:33], off offset:208
	global_load_dwordx2 v[140:141], v[190:191], off offset:224
	global_load_dwordx2 v[142:143], v[32:33], off offset:224
	global_load_dwordx2 v[144:145], v[190:191], off offset:240
	global_load_dwordx2 v[146:147], v[32:33], off offset:240
	s_waitcnt vmcnt(22)
	s_nop 0
	v_mov_b32_e32 v8, v100
	v_mov_b32_e32 v9, v101
	s_nop 0
	v_mov_b32_e32 v30, v102
	v_mov_b32_e32 v31, v103
	v_lshlrev_b32_e32 v28, 16, v8
	v_and_b32_e32 v29, 0xffff0000, v8
	v_lshlrev_b32_e32 v8, 16, v9
	v_and_b32_e32 v9, 0xffff0000, v9
	v_lshlrev_b32_e32 v48, 16, v30
	v_and_b32_e32 v49, 0xffff0000, v30
	v_lshlrev_b32_e32 v30, 16, v31
	v_and_b32_e32 v31, 0xffff0000, v31
	v_pk_fma_f32 v[28:29], v[64:65], v[28:29], v[48:49]
	v_pk_fma_f32 v[8:9], v[50:51], v[8:9], v[30:31]
	v_cvt_pk_bf16_f32 v28, v28, v29
	v_cvt_pk_bf16_f32 v29, v8, v9
	s_waitcnt vmcnt(20)
	s_nop 0
	v_mov_b32_e32 v8, v104
	v_mov_b32_e32 v9, v105
	v_mov_b32_e32 v30, v106
	v_mov_b32_e32 v31, v107
	v_lshlrev_b32_e32 v48, 16, v30
	global_store_dwordx2 v[32:33], v[28:29], off offset:64
	v_lshlrev_b32_e32 v28, 16, v8
	v_and_b32_e32 v29, 0xffff0000, v8
	v_lshlrev_b32_e32 v8, 16, v9
	v_and_b32_e32 v9, 0xffff0000, v9
	v_and_b32_e32 v49, 0xffff0000, v30
	v_lshlrev_b32_e32 v30, 16, v31
	v_and_b32_e32 v31, 0xffff0000, v31
	v_pk_fma_f32 v[28:29], v[66:67], v[28:29], v[48:49]
	v_pk_fma_f32 v[8:9], v[54:55], v[8:9], v[30:31]
	v_cvt_pk_bf16_f32 v28, v28, v29
	v_cvt_pk_bf16_f32 v29, v8, v9
	s_waitcnt vmcnt(19)
	s_nop 0
	v_mov_b32_e32 v8, v108
	v_mov_b32_e32 v9, v109
	v_mov_b32_e32 v30, v110
	v_mov_b32_e32 v31, v111
	v_lshlrev_b32_e32 v48, 16, v30
	global_store_dwordx2 v[32:33], v[28:29], off offset:80
	v_lshlrev_b32_e32 v28, 16, v8
	v_and_b32_e32 v29, 0xffff0000, v8
	v_lshlrev_b32_e32 v8, 16, v9
	v_and_b32_e32 v9, 0xffff0000, v9
	v_and_b32_e32 v49, 0xffff0000, v30
	v_lshlrev_b32_e32 v30, 16, v31
	v_and_b32_e32 v31, 0xffff0000, v31
	v_pk_fma_f32 v[28:29], v[74:75], v[28:29], v[48:49]
	v_pk_fma_f32 v[8:9], v[68:69], v[8:9], v[30:31]
	v_cvt_pk_bf16_f32 v28, v28, v29
	v_cvt_pk_bf16_f32 v29, v8, v9
	s_waitcnt vmcnt(18)
	s_nop 0
	v_mov_b32_e32 v8, v112
	v_mov_b32_e32 v9, v113
	v_mov_b32_e32 v30, v114
	v_mov_b32_e32 v31, v115
	v_lshlrev_b32_e32 v48, 16, v30
	global_store_dwordx2 v[32:33], v[28:29], off offset:96
	v_lshlrev_b32_e32 v28, 16, v8
	v_and_b32_e32 v29, 0xffff0000, v8
	v_lshlrev_b32_e32 v8, 16, v9
	v_and_b32_e32 v9, 0xffff0000, v9
	v_and_b32_e32 v49, 0xffff0000, v30
	v_lshlrev_b32_e32 v30, 16, v31
	v_and_b32_e32 v31, 0xffff0000, v31
	v_pk_fma_f32 v[28:29], v[46:47], v[28:29], v[48:49]
	v_pk_fma_f32 v[8:9], v[44:45], v[8:9], v[30:31]
	v_cvt_pk_bf16_f32 v28, v28, v29
	v_cvt_pk_bf16_f32 v29, v8, v9
	global_store_dwordx2 v[32:33], v[28:29], off offset:112
	s_waitcnt vmcnt(18)
; __device__ __forceinline__ unsigned pk2(float lo, float hi) { f32x2_t v = {lo, hi}; bf16x2_t b = __builtin_convertvector(v, bf16x2_t); return __builtin_bit_cast(unsigned, b); }
; __device__ __forceinline__ float bflo(unsigned u) { return __uint_as_float(u << 16); }
; __device__ __forceinline__ float bfhi(unsigned u) { return __uint_as_float(u & 0xffff0000u); }
; template <int DV, bool ACCUM>
; __device__ __forceinline__ void attn_store(const f32x16 (&o)[DV / 32], const bf16_t* gate_row, bf16_t* merged_row, int h) {
; #pragma unroll
;     for (int db = 0; db < DV / 32; ++db)
; #pragma unroll
;         for (int rg = 0; rg < 4; ++rg) {
;             const int d = 32 * db + 8 * rg + 4 * h;
;             const u32x2 g = *(const u32x2*)(gate_row + d);
;             float v0 = o[db][4 * rg + 0] * bflo(g.x), v1 = o[db][4 * rg + 1] * bfhi(g.x), v2 = o[db][4 * rg + 2] * bflo(g.y), v3 = o[db][4 * rg + 3] * bfhi(g.y);
;             if (ACCUM) { const u32x2 mm = *(const u32x2*)(merged_row + d); v0 += bflo(mm.x); v1 += bfhi(mm.x); v2 += bflo(mm.y); v3 += bfhi(mm.y); }
;             u32x2 w; w.x = pk2(v0, v1); w.y = pk2(v2, v3);
;             *(u32x2*)(merged_row + d) = w;
;             if (rg == 3) __builtin_amdgcn_sched_barrier(0);
;         }
	s_nop 0
	v_mov_b32_e32 v8, v116
	v_mov_b32_e32 v9, v117
	v_mov_b32_e32 v30, v118
	v_mov_b32_e32 v31, v119
	v_lshlrev_b32_e32 v28, 16, v8
	v_and_b32_e32 v29, 0xffff0000, v8
	v_lshlrev_b32_e32 v8, 16, v9
	v_and_b32_e32 v9, 0xffff0000, v9
	v_lshlrev_b32_e32 v44, 16, v30
	v_and_b32_e32 v45, 0xffff0000, v30
	v_lshlrev_b32_e32 v30, 16, v31
	v_and_b32_e32 v31, 0xffff0000, v31
	v_pk_fma_f32 v[28:29], v[42:43], v[28:29], v[44:45]
	v_pk_fma_f32 v[8:9], v[40:41], v[8:9], v[30:31]
	v_cvt_pk_bf16_f32 v28, v28, v29
	v_cvt_pk_bf16_f32 v29, v8, v9
	s_waitcnt vmcnt(16)
	s_nop 0
	v_mov_b32_e32 v8, v120
	v_mov_b32_e32 v9, v121
	v_mov_b32_e32 v30, v122
	v_mov_b32_e32 v31, v123
	v_lshlrev_b32_e32 v40, 16, v30
	global_store_dwordx2 v[32:33], v[28:29], off offset:128
	v_lshlrev_b32_e32 v28, 16, v8
	v_and_b32_e32 v29, 0xffff0000, v8
	v_lshlrev_b32_e32 v8, 16, v9
	v_and_b32_e32 v9, 0xffff0000, v9
	v_and_b32_e32 v41, 0xffff0000, v30
	v_lshlrev_b32_e32 v30, 16, v31
	v_and_b32_e32 v31, 0xffff0000, v31
	v_pk_fma_f32 v[28:29], v[38:39], v[28:29], v[40:41]
	v_pk_fma_f32 v[8:9], v[36:37], v[8:9], v[30:31]
	v_cvt_pk_bf16_f32 v28, v28, v29
	v_cvt_pk_bf16_f32 v29, v8, v9
	s_waitcnt vmcnt(15)
	s_nop 0
	v_mov_b32_e32 v8, v124
	v_mov_b32_e32 v9, v125
	v_mov_b32_e32 v30, v126
	v_mov_b32_e32 v31, v127
	v_lshlrev_b32_e32 v36, 16, v30
	global_store_dwordx2 v[32:33], v[28:29], off offset:144
	v_lshlrev_b32_e32 v28, 16, v8
	v_and_b32_e32 v29, 0xffff0000, v8
	v_lshlrev_b32_e32 v8, 16, v9
	v_and_b32_e32 v9, 0xffff0000, v9
	v_and_b32_e32 v37, 0xffff0000, v30
	v_lshlrev_b32_e32 v30, 16, v31
	v_and_b32_e32 v31, 0xffff0000, v31
	v_pk_fma_f32 v[28:29], v[34:35], v[28:29], v[36:37]
	v_pk_fma_f32 v[8:9], v[26:27], v[8:9], v[30:31]
	v_cvt_pk_bf16_f32 v26, v28, v29
	v_cvt_pk_bf16_f32 v27, v8, v9
	s_waitcnt vmcnt(14)
	s_nop 0
	v_mov_b32_e32 v8, v128
	v_mov_b32_e32 v9, v129
	v_mov_b32_e32 v28, v130
	v_mov_b32_e32 v29, v131
	v_lshlrev_b32_e32 v30, 16, v28
	global_store_dwordx2 v[32:33], v[26:27], off offset:160
	v_lshlrev_b32_e32 v26, 16, v8
	v_and_b32_e32 v27, 0xffff0000, v8
	v_and_b32_e32 v31, 0xffff0000, v28
	v_lshlrev_b32_e32 v8, 16, v9
	v_and_b32_e32 v9, 0xffff0000, v9
	v_pk_fma_f32 v[24:25], v[24:25], v[26:27], v[30:31]
	v_lshlrev_b32_e32 v26, 16, v29
	v_and_b32_e32 v27, 0xffff0000, v29
	v_pk_fma_f32 v[8:9], v[22:23], v[8:9], v[26:27]
	v_cvt_pk_bf16_f32 v22, v24, v25
	v_cvt_pk_bf16_f32 v23, v8, v9
	global_store_dwordx2 v[32:33], v[22:23], off offset:176
	s_waitcnt vmcnt(14)
	s_nop 0
	v_mov_b32_e32 v8, v132
	v_mov_b32_e32 v9, v133
	v_mov_b32_e32 v24, v134
	v_mov_b32_e32 v25, v135
	v_pk_mul_f32 v[2:3], v[0:1], v[2:3] op_sel_hi:[0,1]
	v_pk_mul_f32 v[4:5], v[0:1], v[4:5] op_sel_hi:[0,1]
	v_pk_mul_f32 v[2:3], v[2:3], v[188:189]
	v_pk_mul_f32 v[4:5], v[4:5], v[14:15]
	v_lshlrev_b32_e32 v22, 16, v8
	v_and_b32_e32 v23, 0xffff0000, v8
	v_lshlrev_b32_e32 v26, 16, v24
	v_and_b32_e32 v27, 0xffff0000, v24
	v_lshlrev_b32_e32 v8, 16, v9
	v_and_b32_e32 v9, 0xffff0000, v9
	v_pk_fma_f32 v[20:21], v[20:21], v[22:23], v[26:27]
	v_lshlrev_b32_e32 v22, 16, v25
	v_and_b32_e32 v23, 0xffff0000, v25
	v_pk_fma_f32 v[8:9], v[18:19], v[8:9], v[22:23]
	v_cvt_pk_bf16_f32 v18, v20, v21
	v_cvt_pk_bf16_f32 v19, v8, v9
	s_waitcnt vmcnt(12)
	s_nop 0
	v_mov_b32_e32 v8, v136
	v_mov_b32_e32 v9, v137
	v_mov_b32_e32 v20, v138
	v_mov_b32_e32 v21, v139
	v_lshlrev_b32_e32 v22, 16, v20
	global_store_dwordx2 v[32:33], v[18:19], off offset:192
	v_lshlrev_b32_e32 v18, 16, v8
	v_and_b32_e32 v19, 0xffff0000, v8
	v_and_b32_e32 v23, 0xffff0000, v20
	v_lshlrev_b32_e32 v8, 16, v9
	v_and_b32_e32 v9, 0xffff0000, v9
	v_pk_fma_f32 v[16:17], v[16:17], v[18:19], v[22:23]
	v_lshlrev_b32_e32 v18, 16, v21
	v_and_b32_e32 v19, 0xffff0000, v21
	v_pk_fma_f32 v[8:9], v[12:13], v[8:9], v[18:19]
	v_cvt_pk_bf16_f32 v12, v16, v17
	v_cvt_pk_bf16_f32 v13, v8, v9
	s_waitcnt vmcnt(11)
	s_nop 0
	v_mov_b32_e32 v8, v140
	v_mov_b32_e32 v9, v141
	v_mov_b32_e32 v16, v142
	v_mov_b32_e32 v17, v143
	v_lshlrev_b32_e32 v18, 16, v16
	global_store_dwordx2 v[32:33], v[12:13], off offset:208
	v_lshlrev_b32_e32 v12, 16, v8
	v_and_b32_e32 v13, 0xffff0000, v8
	v_and_b32_e32 v19, 0xffff0000, v16
	v_lshlrev_b32_e32 v8, 16, v9
	v_and_b32_e32 v9, 0xffff0000, v9
	v_pk_fma_f32 v[10:11], v[10:11], v[12:13], v[18:19]
	v_lshlrev_b32_e32 v12, 16, v17
	v_and_b32_e32 v13, 0xffff0000, v17
	v_pk_fma_f32 v[6:7], v[6:7], v[8:9], v[12:13]
	v_cvt_pk_bf16_f32 v8, v10, v11
	v_cvt_pk_bf16_f32 v9, v6, v7
	global_store_dwordx2 v[32:33], v[8:9], off offset:224
	s_waitcnt vmcnt(11)
	s_nop 0
	v_mov_b32_e32 v6, v144
	v_mov_b32_e32 v7, v145
	s_nop 0
	v_mov_b32_e32 v8, v146
	v_mov_b32_e32 v9, v147
	v_lshlrev_b32_e32 v10, 16, v6
	v_and_b32_e32 v11, 0xffff0000, v6
	v_lshlrev_b32_e32 v12, 16, v8
	v_and_b32_e32 v13, 0xffff0000, v8
	v_lshlrev_b32_e32 v6, 16, v7
	v_and_b32_e32 v7, 0xffff0000, v7
	v_lshlrev_b32_e32 v8, 16, v9
	v_and_b32_e32 v9, 0xffff0000, v9
	v_pk_fma_f32 v[2:3], v[2:3], v[10:11], v[12:13]
	v_pk_fma_f32 v[4:5], v[4:5], v[6:7], v[8:9]
	v_cvt_pk_bf16_f32 v2, v2, v3
	v_cvt_pk_bf16_f32 v3, v4, v5
	global_store_dwordx2 v[32:33], v[2:3], off offset:240
	v_readlane_b32 s0, v254, 0
	s_add_i32 s24, s24, s30
	s_add_i32 s23, s23, s0
	s_cmpk_gt_i32 s24, 0x3ff
	s_cbranch_scc1 .LBB0_1001
